# h9 + layer-0 f32 norm loop: all 12 row loads issued together and next row prefetched
# baseline (speedup 1.0000x reference)
; __device__ __forceinline__ int opaque_tid() { int t = threadIdx.x; asm volatile("" : "+v"(t)); return t; }
; __device__ __forceinline__ unsigned cvt_pk_bf16(float lo, float hi) { f32x2_t v = {lo, hi}; bf16x2_t b = __builtin_convertvector(v, bf16x2_t); return __builtin_bit_cast(unsigned, b); }
; __device__ __forceinline__ void norm_phase(const float* x, const float* gain, const float* shift, const float* scale, bf16* H, int bid, int ngw) {
;     const int tid = opaque_tid(), lane = tid & 63, gw = bid * 8 + __builtin_amdgcn_readfirstlane(tid >> 6);
;     f32x4 gv[4];
; #pragma unroll
;     for (int j = 0; j < 4; ++j) gv[j] = *(const f32x4*)(gain + 4 * lane + 256 * j);
;     for (int row = gw; row < TOK; row += ngw) {
;         const f32x4* xr = (const f32x4*)(x + (size_t)row * 1024) + lane;
;         const int b = row >> 11;
;         f32x4 v[4]; float s = 0.f;
; #pragma unroll
;         for (int j = 0; j < 4; ++j) { v[j] = xr[64 * j]; s += (v[j].x * v[j].x + v[j].y * v[j].y) + (v[j].z * v[j].z + v[j].w * v[j].w); }
;         const float rstd = rsqrtf(wave_sum(s, lane) * (1.0f / 1024.0f) + RMS_EPS);
;         unsigned long long* o8 = (unsigned long long*)(H + (size_t)row * 1024) + lane;
; #pragma unroll
;         for (int j = 0; j < 4; ++j) {
;             const f32x4 sc = *(const f32x4*)(scale + (size_t)b * 6144 + 4 * lane + 256 * j), sh = *(const f32x4*)(shift + (size_t)b * 6144 + 4 * lane + 256 * j);
;             const f32x4 y = v[j] * rstd * gv[j] * (sc + 1.0f) + sh;
;             o8[64 * j] = (unsigned long long)cvt_pk_bf16(y.x, y.y) | ((unsigned long long)cvt_pk_bf16(y.z, y.w) << 32);
;         }
;     }
.LBB0_185:
	s_andn2_b64 vcc, exec, s[0:1]
	s_cbranch_vccnz .LBB0_189
	v_mov_b32_e32 v0, v206
	s_nop 0
	v_readfirstlane_b32 s0, v0
	s_ashr_i32 s1, s0, 6
	s_add_i32 s0, s1, s70
	s_cmp_gt_i32 s0, 0xffff
	s_cbranch_scc1 .LBB0_189
	v_and_b32_e32 v22, 63, v0
	v_readlane_b32 s4, v254, 26
	v_lshlrev_b32_e32 v0, 4, v22
	v_readlane_b32 s5, v254, 27
	s_nop 4
	global_load_dwordx4 v[2:5], v0, s[4:5]
	global_load_dwordx4 v[6:9], v0, s[4:5] offset:1024
	global_load_dwordx4 v[10:13], v0, s[4:5] offset:2048
	global_load_dwordx4 v[14:17], v0, s[4:5] offset:3072
	v_readlane_b32 s2, v254, 59
	v_lshlrev_b32_e32 v18, 2, v22
	v_readlane_b32 s3, v254, 60
	v_xor_b32_e32 v26, 4, v18
	v_xor_b32_e32 v27, 8, v18
	v_xor_b32_e32 v28, 16, v18
	v_xor_b32_e32 v29, 32, v18
	v_xor_b32_e32 v30, 64, v18
	v_xor_b32_e32 v31, 0x80, v18
	v_lshl_add_u64 v[18:19], s[2:3], 0, v[0:1]
	s_mov_b64 s[2:3], 0x1000
	v_lshl_add_u64 v[20:21], v[18:19], 0, s[2:3]
	s_ashr_i32 s3, s1, 31
	s_add_u32 s2, s70, s1
	v_readlane_b32 s1, v254, 20
	s_addc_u32 s3, s1, s3
	s_lshl_b64 s[4:5], s[2:3], 11
	s_add_u32 s4, s54, s4
	v_lshlrev_b32_e32 v22, 3, v22
	v_mov_b32_e32 v23, v1
	s_addc_u32 s5, s55, s5
	v_lshl_add_u64 v[22:23], s[4:5], 0, v[22:23]
	s_mov_b64 s[4:5], 0x8000000
	v_lshl_add_u64 v[22:23], v[22:23], 0, s[4:5]
	s_lshl_b64 s[2:3], s[2:3], 12
	v_readlane_b32 s4, v254, 2
	v_readlane_b32 s6, v254, 28
	v_readlane_b32 s7, v254, 29
	v_readlane_b32 s5, v254, 3
	s_add_u32 s2, s4, s2
	s_addc_u32 s3, s5, s3
	v_readlane_b32 s4, v254, 44
	v_readlane_b32 s6, v254, 46
	v_lshl_add_u64 v[24:25], s[2:3], 0, v[0:1]
	v_readlane_b32 s5, v254, 45
	v_readlane_b32 s7, v254, 47
	s_ashr_i32 s1, s0, 11
	v_mad_i64_i32 v[56:57], s[2:3], s1, v252, v[20:21]
	v_mad_i64_i32 v[58:59], s[2:3], s1, v252, v[18:19]
	global_load_dwordx4 v[100:103], v[24:25], off
	global_load_dwordx4 v[104:107], v[24:25], off offset:1024
	global_load_dwordx4 v[108:111], v[24:25], off offset:3072
	global_load_dwordx4 v[112:115], v[24:25], off offset:2048
	global_load_dwordx4 v[116:119], v[56:57], off
	global_load_dwordx4 v[120:123], v[58:59], off
	global_load_dwordx4 v[124:127], v[56:57], off offset:1024
	global_load_dwordx4 v[128:131], v[58:59], off offset:1024
	global_load_dwordx4 v[132:135], v[56:57], off offset:2048
	global_load_dwordx4 v[136:139], v[58:59], off offset:2048
	global_load_dwordx4 v[140:143], v[56:57], off offset:3072
	global_load_dwordx4 v[144:147], v[58:59], off offset:3072
	s_waitcnt vmcnt(0)
.LBB0_188:
	v_mov_b64_e32 v[32:33], v[100:101]
	v_mov_b64_e32 v[34:35], v[102:103]
	v_mov_b64_e32 v[36:37], v[104:105]
	v_mov_b64_e32 v[38:39], v[106:107]
	v_mov_b64_e32 v[40:41], v[108:109]
	v_mov_b64_e32 v[42:43], v[110:111]
	v_mov_b64_e32 v[44:45], v[112:113]
	v_mov_b64_e32 v[46:47], v[114:115]
	v_mov_b64_e32 v[48:49], v[116:117]
	v_mov_b64_e32 v[50:51], v[118:119]
	v_mov_b64_e32 v[52:53], v[120:121]
	v_mov_b64_e32 v[54:55], v[122:123]
	v_mov_b64_e32 v[76:77], v[124:125]
	v_mov_b64_e32 v[78:79], v[126:127]
	v_mov_b64_e32 v[80:81], v[128:129]
	v_mov_b64_e32 v[82:83], v[130:131]
	v_mov_b64_e32 v[84:85], v[132:133]
	v_mov_b64_e32 v[86:87], v[134:135]
	v_mov_b64_e32 v[88:89], v[136:137]
	v_mov_b64_e32 v[90:91], v[138:139]
	v_mov_b64_e32 v[92:93], v[140:141]
	v_mov_b64_e32 v[94:95], v[142:143]
	v_mov_b64_e32 v[96:97], v[144:145]
	v_mov_b64_e32 v[98:99], v[146:147]
	s_add_i32 s0, s0, s68
	s_cmp_gt_i32 s0, 0xffff
	s_cbranch_scc1 .Lnorm0_nopf
	v_lshl_add_u64 v[24:25], v[24:25], 0, s[6:7]
	s_ashr_i32 s1, s0, 11
	v_mad_i64_i32 v[56:57], s[2:3], s1, v252, v[20:21]
	v_mad_i64_i32 v[58:59], s[2:3], s1, v252, v[18:19]
	global_load_dwordx4 v[100:103], v[24:25], off
	global_load_dwordx4 v[104:107], v[24:25], off offset:1024
	global_load_dwordx4 v[108:111], v[24:25], off offset:3072
	global_load_dwordx4 v[112:115], v[24:25], off offset:2048
	global_load_dwordx4 v[116:119], v[56:57], off
	global_load_dwordx4 v[120:123], v[58:59], off
	global_load_dwordx4 v[124:127], v[56:57], off offset:1024
	global_load_dwordx4 v[128:131], v[58:59], off offset:1024
	global_load_dwordx4 v[132:135], v[56:57], off offset:2048
	global_load_dwordx4 v[136:139], v[58:59], off offset:2048
	global_load_dwordx4 v[140:143], v[56:57], off offset:3072
	global_load_dwordx4 v[144:147], v[58:59], off offset:3072
; __device__ __forceinline__ unsigned cvt_pk_bf16(float lo, float hi) { f32x2_t v = {lo, hi}; bf16x2_t b = __builtin_convertvector(v, bf16x2_t); return __builtin_bit_cast(unsigned, b); }
; __device__ __forceinline__ void norm_phase(const float* x, const float* gain, const float* shift, const float* scale, bf16* H, int bid, int ngw) {
;     ...
; #pragma unroll
;         for (int j = 0; j < 4; ++j) { v[j] = xr[64 * j]; s += (v[j].x * v[j].x + v[j].y * v[j].y) + (v[j].z * v[j].z + v[j].w * v[j].w); }
;         const float rstd = rsqrtf(wave_sum(s, lane) * (1.0f / 1024.0f) + RMS_EPS);
;         unsigned long long* o8 = (unsigned long long*)(H + (size_t)row * 1024) + lane;
; #pragma unroll
;         for (int j = 0; j < 4; ++j) {
;             const f32x4 sc = *(const f32x4*)(scale + (size_t)b * 6144 + 4 * lane + 256 * j), sh = *(const f32x4*)(shift + (size_t)b * 6144 + 4 * lane + 256 * j);
;             const f32x4 y = v[j] * rstd * gv[j] * (sc + 1.0f) + sh;
;             o8[64 * j] = (unsigned long long)cvt_pk_bf16(y.x, y.y) | ((unsigned long long)cvt_pk_bf16(y.z, y.w) << 32);
;         }
;     }
.Lnorm0_nopf:
	v_pk_mul_f32 v[60:61], v[32:33], v[32:33]
	v_pk_fma_f32 v[60:61], v[34:35], v[34:35], v[60:61]
	v_pk_fma_f32 v[60:61], v[36:37], v[36:37], v[60:61]
	v_pk_fma_f32 v[60:61], v[38:39], v[38:39], v[60:61]
	v_pk_fma_f32 v[60:61], v[40:41], v[40:41], v[60:61]
	v_pk_fma_f32 v[60:61], v[42:43], v[42:43], v[60:61]
	v_pk_fma_f32 v[60:61], v[44:45], v[44:45], v[60:61]
	v_pk_fma_f32 v[60:61], v[46:47], v[46:47], v[60:61]
	s_nop 0
	v_add_f32_e32 v0, v60, v61
	ds_bpermute_b32 v60, v26, v0
	s_waitcnt lgkmcnt(0)
	v_add_f32_e32 v0, v0, v60
	ds_bpermute_b32 v60, v27, v0
	s_waitcnt lgkmcnt(0)
	v_add_f32_e32 v0, v0, v60
	ds_bpermute_b32 v60, v28, v0
	s_waitcnt lgkmcnt(0)
	v_add_f32_e32 v0, v0, v60
	ds_bpermute_b32 v60, v29, v0
	s_waitcnt lgkmcnt(0)
	v_add_f32_e32 v0, v0, v60
	ds_bpermute_b32 v60, v30, v0
	s_waitcnt lgkmcnt(0)
	v_add_f32_e32 v0, v0, v60
	ds_bpermute_b32 v60, v31, v0
	s_waitcnt lgkmcnt(0)
	v_add_f32_e32 v0, v0, v60
	v_fmamk_f32 v0, v0, 0x3a800000, v207
	v_mul_f32_e32 v60, 0x4b800000, v0
	v_cmp_gt_f32_e32 vcc, s87, v0
	s_nop 1
	v_cndmask_b32_e32 v0, v0, v60, vcc
	v_rsq_f32_e32 v0, v0
	s_nop 0
	v_mul_f32_e32 v60, 0x45800000, v0
	v_cndmask_b32_e32 v0, v0, v60, vcc
	s_nop 0
	v_pk_mul_f32 v[32:33], v[32:33], v[0:1] op_sel_hi:[1,0]
	v_pk_mul_f32 v[34:35], v[34:35], v[0:1] op_sel_hi:[1,0]
	v_pk_add_f32 v[48:49], v[48:49], 1.0 op_sel_hi:[1,0]
	v_pk_add_f32 v[50:51], v[50:51], 1.0 op_sel_hi:[1,0]
	v_pk_mul_f32 v[32:33], v[2:3], v[32:33]
	v_pk_mul_f32 v[34:35], v[4:5], v[34:35]
	v_pk_fma_f32 v[32:33], v[48:49], v[32:33], v[52:53]
	v_pk_fma_f32 v[34:35], v[50:51], v[34:35], v[54:55]
	s_nop 0
	v_cvt_pk_bf16_f32 v62, v32, v33
	v_cvt_pk_bf16_f32 v63, v34, v35
	global_store_dwordx2 v[22:23], v[62:63], off
	v_pk_mul_f32 v[36:37], v[36:37], v[0:1] op_sel_hi:[1,0]
	v_pk_mul_f32 v[38:39], v[38:39], v[0:1] op_sel_hi:[1,0]
	v_pk_add_f32 v[76:77], v[76:77], 1.0 op_sel_hi:[1,0]
	v_pk_add_f32 v[78:79], v[78:79], 1.0 op_sel_hi:[1,0]
	v_pk_mul_f32 v[36:37], v[6:7], v[36:37]
	v_pk_mul_f32 v[38:39], v[8:9], v[38:39]
	v_pk_fma_f32 v[36:37], v[76:77], v[36:37], v[80:81]
	v_pk_fma_f32 v[38:39], v[78:79], v[38:39], v[82:83]
	s_nop 0
	v_cvt_pk_bf16_f32 v64, v36, v37
	v_cvt_pk_bf16_f32 v65, v38, v39
	global_store_dwordx2 v[22:23], v[64:65], off offset:512
	v_pk_mul_f32 v[44:45], v[44:45], v[0:1] op_sel_hi:[1,0]
	v_pk_mul_f32 v[46:47], v[46:47], v[0:1] op_sel_hi:[1,0]
	v_pk_add_f32 v[84:85], v[84:85], 1.0 op_sel_hi:[1,0]
	v_pk_add_f32 v[86:87], v[86:87], 1.0 op_sel_hi:[1,0]
	v_pk_mul_f32 v[44:45], v[10:11], v[44:45]
	v_pk_mul_f32 v[46:47], v[12:13], v[46:47]
	v_pk_fma_f32 v[44:45], v[84:85], v[44:45], v[88:89]
	v_pk_fma_f32 v[46:47], v[86:87], v[46:47], v[90:91]
	s_nop 0
	v_cvt_pk_bf16_f32 v66, v44, v45
	v_cvt_pk_bf16_f32 v67, v46, v47
	global_store_dwordx2 v[22:23], v[66:67], off offset:1024
	v_pk_mul_f32 v[40:41], v[40:41], v[0:1] op_sel_hi:[1,0]
	v_pk_mul_f32 v[42:43], v[42:43], v[0:1] op_sel_hi:[1,0]
	v_pk_add_f32 v[92:93], v[92:93], 1.0 op_sel_hi:[1,0]
	v_pk_add_f32 v[94:95], v[94:95], 1.0 op_sel_hi:[1,0]
	v_pk_mul_f32 v[40:41], v[14:15], v[40:41]
	v_pk_mul_f32 v[42:43], v[16:17], v[42:43]
	v_pk_fma_f32 v[40:41], v[92:93], v[40:41], v[96:97]
	v_pk_fma_f32 v[42:43], v[94:95], v[42:43], v[98:99]
	s_nop 0
	v_cvt_pk_bf16_f32 v68, v40, v41
	v_cvt_pk_bf16_f32 v69, v42, v43
	global_store_dwordx2 v[22:23], v[68:69], off offset:1536
	v_lshl_add_u64 v[22:23], v[22:23], 0, s[4:5]
	s_cmp_gt_i32 s0, 0xffff
	s_waitcnt vmcnt(4)
	s_cbranch_scc0 .LBB0_188
